# attention phase: static s_setprio 1 for the younger half-workgroup (waves 4-7), reset at phase exit; on top of max-tree softmax
# baseline (speedup 1.0000x reference)
; #define PH(n) if ((n) > a.ph_lo && (n) < a.ph_hi) cg::this_grid().sync(); if ((n) >= a.ph_lo && (n) < a.ph_hi)
; __device__ __forceinline__ void diff_attn_units(const Args& a, unsigned char* lds) {
;     const bf16_t* GT = (const bf16_t*)(a.ws + WS_GATE);
;     bf16_t* BRc = (bf16_t*)(a.ws + WS_BRANCH);
;     const bf16_t* KB = (const bf16_t*)(a.ws + WS_KB);
;     const bf16_t* VB = (const bf16_t*)(a.ws + WS_VB);
;     const bf16_t* SK = (const bf16_t*)((const unsigned char*)a.out + T_SK);
;     const bf16_t* SV = (const bf16_t*)((const unsigned char*)a.out + T_SV);
;     float s1 = 0.f, s2 = 0.f;
;     for (int i = 0; i < 64; ++i) { s1 += a.in[27][i] * a.in[28][i]; s2 += a.in[29][i] * a.in[30][i]; }
;     const float lam = __expf(s1) - __expf(s2) + 0.35550907f;
; __global__ void __launch_bounds__(NTHR) mega(Args a) {
;     ...
;     PH(8) { const Args A = load_args(); unsigned char* ws = A.ws; unsigned char* ob = (unsigned char*)A.out; (void)ws; (void)ob; diff_attn_units(A, lds); mem_attn_units(A, lds, 1, blockIdx.x, gridDim.x); }
.LBB0_1140:
	s_cmp_lt_i32 s48, 9
	s_cselect_b64 s[50:51], -1, 0
	s_and_b64 s[4:5], s[50:51], s[4:5]
	s_andn2_b64 vcc, exec, s[4:5]
	s_cbranch_vccnz .LBB0_1207
	v_readfirstlane_b32 s89, v179
	s_nop 0
	s_cmp_lt_u32 s89, 4
	s_cbranch_scc1 .Lattn_noprio
	s_setprio 1
.Lattn_noprio:
	s_mov_b64 s[12:13], s[0:1]
	s_load_dwordx8 s[4:11], s[12:13], 0xd8
	s_load_dwordx4 s[44:47], s[12:13], 0xf8
	s_load_dwordx2 s[54:55], s[12:13], 0x108
	v_mov_b32_e32 v2, 0
	s_mov_b64 s[12:13], 0
	v_mov_b32_e32 v0, 0
	v_mov_b32_e32 v1, v2

.LBB0_1207:
	s_setprio 0
	s_cmp_gt_i32 s49, 9
	s_cselect_b64 s[4:5], -1, 0
	s_and_b64 s[6:7], s[50:51], s[4:5]
	s_andn2_b64 vcc, exec, s[6:7]
	s_cbranch_vccnz .LBB0_1219
	v_or_b32_e32 v0, v173, v169
	s_movk_i32 s3, 0x3ff
	v_and_or_b32 v0, v0, s3, v170
	v_cmp_eq_u32_e32 vcc, 0, v0
	s_waitcnt vmcnt(0) lgkmcnt(0)
	s_barrier
	s_and_saveexec_b64 s[6:7], vcc
	s_cbranch_execz .LBB0_1218
	buffer_wbl2 sc1
	s_load_dwordx2 s[8:9], s[0:1], 0x170
	v_mov_b32_e32 v2, 0
	s_mov_b64 s[10:11], exec
	v_mbcnt_lo_u32_b32 v1, s10, 0
	v_mbcnt_hi_u32_b32 v1, s11, v1
	s_waitcnt lgkmcnt(0)
	global_load_dword v0, v2, s[8:9] offset:40
	v_cmp_eq_u32_e32 vcc, 0, v1
	s_and_saveexec_b64 s[12:13], vcc
	s_cbranch_execz .LBB0_1211
	s_bcnt1_i32_b64 s3, s[10:11]
	v_mov_b32_e32 v3, s3
	global_atomic_add v3, v2, v3, s[8:9] offset:32 sc0
